# y2 + LN1 router: 127 ds_read_b128 round trips software-pipelined (6 reads in flight in a ring of free VGPR quads, counted lgkmcnt)
# speedup vs baseline: 1.0103x; 1.0103x over previous
; #define LAS __attribute__((address_space(3)))
; __device__ __forceinline__ void ph_ln1_router(const Ctx& X, CArgs a, int l, int nrows) {
;     ...
;         float lgt[2][16];
; #pragma unroll
;         for (int q = 0; q < 2; ++q) {
;             unsigned cq = l4; asm volatile("" : "+v"(cq));
; #pragma unroll
;             for (int e = 0; e < 16; ++e) lgt[q][e] = 0.f;
; #pragma unroll
;             for (int j = 0; j < 4; ++j)
; #pragma unroll
;                 for (int e = 0; e < 16; ++e) { const f32x4 wr = *(const LAS f32x4*)(WR + e * 1024 + cq + 256u * j);
;                     lgt[q][e] += (v[q][j][0] * wr[0] + v[q][j][1] * wr[1]) + (v[q][j][2] * wr[2] + v[q][j][3] * wr[3]);
;                     asm volatile("" : "+v"(lgt[q][e]));
;                     if ((e & 7) == 7) __builtin_amdgcn_sched_barrier(0); }
;         }
.LBB0_1429:
	v_mov_b32_e32 v0, v64
	s_nop 0
	v_lshl_add_u32 v90, v0, 2, 0
	s_waitcnt lgkmcnt(0)
	ds_read_b128 v[130:133], v90
	ds_read_b128 v[134:137], v90 offset:4096
	ds_read_b128 v[138:141], v90 offset:8192
	ds_read_b128 v[142:145], v90 offset:12288
	ds_read_b128 v[146:149], v90 offset:16384
	ds_read_b128 v[122:125], v90 offset:20480
	s_waitcnt lgkmcnt(5)
	v_mul_f32_e32 v0, v89, v131
	v_mul_f32_e32 v65, v87, v133
	v_fmac_f32_e32 v0, v88, v130
	v_fmac_f32_e32 v65, v86, v132
	ds_read_b128 v[130:133], v90 offset:24576
	v_add_f32_e32 v0, v0, v65
	v_add_f32_e32 v0, 0, v0
	s_waitcnt lgkmcnt(5)
	v_mul_f32_e32 v65, v89, v135
	v_mul_f32_e32 v135, v87, v137
	v_fmac_f32_e32 v65, v88, v134
	v_fmac_f32_e32 v135, v86, v136
	v_add_f32_e32 v65, v65, v135
	ds_read_b128 v[134:137], v90 offset:28672
	v_add_f32_e32 v65, 0, v65
	s_waitcnt lgkmcnt(5)
	v_mul_f32_e32 v139, v89, v139
	v_mul_f32_e32 v141, v87, v141
	v_fmac_f32_e32 v139, v88, v138
	v_fmac_f32_e32 v141, v86, v140
	v_add_f32_e32 v138, v139, v141
	v_add_f32_e32 v91, 0, v138
	ds_read_b128 v[138:141], v90 offset:32768
	s_waitcnt lgkmcnt(5)
	v_mul_f32_e32 v143, v89, v143
	v_mul_f32_e32 v145, v87, v145
	v_fmac_f32_e32 v143, v88, v142
	v_fmac_f32_e32 v145, v86, v144
	v_add_f32_e32 v142, v143, v145
	v_add_f32_e32 v92, 0, v142
	ds_read_b128 v[142:145], v90 offset:36864
	s_waitcnt lgkmcnt(5)
	v_mul_f32_e32 v147, v89, v147
	v_mul_f32_e32 v149, v87, v149
	v_fmac_f32_e32 v147, v88, v146
	v_fmac_f32_e32 v149, v86, v148
	v_add_f32_e32 v146, v147, v149
	v_add_f32_e32 v93, 0, v146
	ds_read_b128 v[146:149], v90 offset:40960
	s_waitcnt lgkmcnt(5)
	v_mul_f32_e32 v123, v89, v123
	v_mul_f32_e32 v125, v87, v125
	v_fmac_f32_e32 v123, v88, v122
	v_fmac_f32_e32 v125, v86, v124
	v_add_f32_e32 v122, v123, v125
	v_add_f32_e32 v94, 0, v122
	ds_read_b128 v[122:125], v90 offset:45056
	s_waitcnt lgkmcnt(5)
	v_mul_f32_e32 v131, v89, v131
	v_mul_f32_e32 v133, v87, v133
	v_fmac_f32_e32 v131, v88, v130
	v_fmac_f32_e32 v133, v86, v132
	v_add_f32_e32 v130, v131, v133
	v_add_f32_e32 v95, 0, v130
	ds_read_b128 v[130:133], v90 offset:49152
	s_waitcnt lgkmcnt(5)
	v_mul_f32_e32 v135, v89, v135
	v_mul_f32_e32 v137, v87, v137
	v_fmac_f32_e32 v135, v88, v134
	v_fmac_f32_e32 v137, v86, v136
	v_add_f32_e32 v134, v135, v137
	v_add_f32_e32 v96, 0, v134
	ds_read_b128 v[134:137], v90 offset:53248
	s_waitcnt lgkmcnt(5)
	v_mul_f32_e32 v139, v89, v139
	v_mul_f32_e32 v141, v87, v141
	v_fmac_f32_e32 v139, v88, v138
	v_fmac_f32_e32 v141, v86, v140
	v_add_f32_e32 v138, v139, v141
	v_add_f32_e32 v97, 0, v138
	ds_read_b128 v[138:141], v90 offset:57344
	s_waitcnt lgkmcnt(5)
	v_mul_f32_e32 v143, v89, v143
	v_mul_f32_e32 v145, v87, v145
	v_fmac_f32_e32 v143, v88, v142
	v_fmac_f32_e32 v145, v86, v144
	v_add_f32_e32 v142, v143, v145
	v_add_f32_e32 v98, 0, v142
	ds_read_b128 v[142:145], v90 offset:61440
	s_waitcnt lgkmcnt(5)
	v_mul_f32_e32 v147, v89, v147
	v_mul_f32_e32 v149, v87, v149
	v_fmac_f32_e32 v147, v88, v146
	v_fmac_f32_e32 v149, v86, v148
	v_add_f32_e32 v146, v147, v149
	v_add_f32_e32 v99, 0, v146
	ds_read_b128 v[146:149], v90 offset:1024
	s_waitcnt lgkmcnt(5)
	v_mul_f32_e32 v123, v89, v123
	v_mul_f32_e32 v125, v87, v125
	v_fmac_f32_e32 v123, v88, v122
	v_fmac_f32_e32 v125, v86, v124
	v_add_f32_e32 v122, v123, v125
	v_add_f32_e32 v100, 0, v122
	ds_read_b128 v[122:125], v90 offset:5120
	s_waitcnt lgkmcnt(5)
	v_mul_f32_e32 v131, v89, v131
	v_mul_f32_e32 v133, v87, v133
	v_fmac_f32_e32 v131, v88, v130
	v_fmac_f32_e32 v133, v86, v132
	v_add_f32_e32 v130, v131, v133
	v_add_f32_e32 v101, 0, v130
	ds_read_b128 v[130:133], v90 offset:9216
	s_waitcnt lgkmcnt(5)
	v_mul_f32_e32 v135, v89, v135
	v_mul_f32_e32 v137, v87, v137
	v_fmac_f32_e32 v135, v88, v134
	v_fmac_f32_e32 v137, v86, v136
	v_add_f32_e32 v134, v135, v137
	v_add_f32_e32 v102, 0, v134
	ds_read_b128 v[134:137], v90 offset:13312
	s_waitcnt lgkmcnt(5)
	v_mul_f32_e32 v139, v89, v139
	v_mul_f32_e32 v141, v87, v141
	v_fmac_f32_e32 v139, v88, v138
	v_fmac_f32_e32 v141, v86, v140
	v_add_f32_e32 v138, v139, v141
	v_add_f32_e32 v103, 0, v138
	ds_read_b128 v[138:141], v90 offset:17408
	s_waitcnt lgkmcnt(5)
	v_mul_f32_e32 v143, v89, v143
	v_mul_f32_e32 v145, v87, v145
	v_fmac_f32_e32 v143, v88, v142
	v_fmac_f32_e32 v145, v86, v144
	v_add_f32_e32 v142, v143, v145
	v_add_f32_e32 v86, 0, v142
	ds_read_b128 v[142:145], v90 offset:21504
	s_waitcnt lgkmcnt(5)
	v_mul_f32_e32 v147, v85, v147
	v_mul_f32_e32 v149, v83, v149
	v_fmac_f32_e32 v147, v84, v146
	v_fmac_f32_e32 v149, v82, v148
	v_add_f32_e32 v146, v147, v149
	v_add_f32_e32 v0, v0, v146
	ds_read_b128 v[146:149], v90 offset:25600
	s_waitcnt lgkmcnt(5)
	v_mul_f32_e32 v123, v85, v123
	v_mul_f32_e32 v125, v83, v125
	v_fmac_f32_e32 v123, v84, v122
	v_fmac_f32_e32 v125, v82, v124
	v_add_f32_e32 v122, v123, v125
	v_add_f32_e32 v65, v65, v122
	ds_read_b128 v[122:125], v90 offset:29696
	s_waitcnt lgkmcnt(5)
	v_mul_f32_e32 v131, v85, v131
	v_mul_f32_e32 v133, v83, v133
	v_fmac_f32_e32 v131, v84, v130
	v_fmac_f32_e32 v133, v82, v132
	v_add_f32_e32 v130, v131, v133
	v_add_f32_e32 v87, v91, v130
	ds_read_b128 v[130:133], v90 offset:33792
	s_waitcnt lgkmcnt(5)
	v_mul_f32_e32 v135, v85, v135
	v_mul_f32_e32 v137, v83, v137
	v_fmac_f32_e32 v135, v84, v134
	v_fmac_f32_e32 v137, v82, v136
	v_add_f32_e32 v134, v135, v137
	v_add_f32_e32 v88, v92, v134
	ds_read_b128 v[134:137], v90 offset:37888
	s_waitcnt lgkmcnt(5)
	v_mul_f32_e32 v139, v85, v139
	v_mul_f32_e32 v141, v83, v141
	v_fmac_f32_e32 v139, v84, v138
	v_fmac_f32_e32 v141, v82, v140
	v_add_f32_e32 v138, v139, v141
	v_add_f32_e32 v89, v93, v138
	ds_read_b128 v[138:141], v90 offset:41984
	s_waitcnt lgkmcnt(5)
; #define LAS __attribute__((address_space(3)))
; __device__ __forceinline__ void ph_ln1_router(const Ctx& X, CArgs a, int l, int nrows) {
;     ...
; #pragma unroll
;             for (int j = 0; j < 4; ++j)
; #pragma unroll
;                 for (int e = 0; e < 16; ++e) { const f32x4 wr = *(const LAS f32x4*)(WR + e * 1024 + cq + 256u * j);
;                     lgt[q][e] += (v[q][j][0] * wr[0] + v[q][j][1] * wr[1]) + (v[q][j][2] * wr[2] + v[q][j][3] * wr[3]);
;                     asm volatile("" : "+v"(lgt[q][e]));
;                     if ((e & 7) == 7) __builtin_amdgcn_sched_barrier(0); }
	v_mul_f32_e32 v143, v85, v143
	v_mul_f32_e32 v145, v83, v145
	v_fmac_f32_e32 v143, v84, v142
	v_fmac_f32_e32 v145, v82, v144
	v_add_f32_e32 v142, v143, v145
	v_add_f32_e32 v91, v94, v142
	ds_read_b128 v[142:145], v90 offset:46080
	s_waitcnt lgkmcnt(5)
	v_mul_f32_e32 v147, v85, v147
	v_mul_f32_e32 v149, v83, v149
	v_fmac_f32_e32 v147, v84, v146
	v_fmac_f32_e32 v149, v82, v148
	v_add_f32_e32 v146, v147, v149
	v_add_f32_e32 v92, v95, v146
	ds_read_b128 v[146:149], v90 offset:50176
	s_waitcnt lgkmcnt(5)
	v_mul_f32_e32 v123, v85, v123
	v_mul_f32_e32 v125, v83, v125
	v_fmac_f32_e32 v123, v84, v122
	v_fmac_f32_e32 v125, v82, v124
	v_add_f32_e32 v122, v123, v125
	v_add_f32_e32 v93, v96, v122
	ds_read_b128 v[122:125], v90 offset:54272
	s_waitcnt lgkmcnt(5)
	v_mul_f32_e32 v131, v85, v131
	v_mul_f32_e32 v133, v83, v133
	v_fmac_f32_e32 v131, v84, v130
	v_fmac_f32_e32 v133, v82, v132
	v_add_f32_e32 v130, v131, v133
	v_add_f32_e32 v94, v97, v130
	ds_read_b128 v[130:133], v90 offset:58368
	s_waitcnt lgkmcnt(5)
	v_mul_f32_e32 v135, v85, v135
	v_mul_f32_e32 v137, v83, v137
	v_fmac_f32_e32 v135, v84, v134
	v_fmac_f32_e32 v137, v82, v136
	v_add_f32_e32 v134, v135, v137
	v_add_f32_e32 v95, v98, v134
	ds_read_b128 v[134:137], v90 offset:62464
	s_waitcnt lgkmcnt(5)
	v_mul_f32_e32 v139, v85, v139
	v_mul_f32_e32 v141, v83, v141
	v_fmac_f32_e32 v139, v84, v138
	v_fmac_f32_e32 v141, v82, v140
	v_add_f32_e32 v138, v139, v141
	v_add_f32_e32 v96, v99, v138
	ds_read_b128 v[138:141], v90 offset:2048
	s_waitcnt lgkmcnt(5)
	v_mul_f32_e32 v143, v85, v143
	v_mul_f32_e32 v145, v83, v145
	v_fmac_f32_e32 v143, v84, v142
	v_fmac_f32_e32 v145, v82, v144
	v_add_f32_e32 v142, v143, v145
	v_add_f32_e32 v97, v100, v142
	ds_read_b128 v[142:145], v90 offset:6144
	s_waitcnt lgkmcnt(5)
	v_mul_f32_e32 v147, v85, v147
	v_mul_f32_e32 v149, v83, v149
	v_fmac_f32_e32 v147, v84, v146
	v_fmac_f32_e32 v149, v82, v148
	v_add_f32_e32 v146, v147, v149
	v_add_f32_e32 v98, v101, v146
	ds_read_b128 v[146:149], v90 offset:10240
	s_waitcnt lgkmcnt(5)
	v_mul_f32_e32 v123, v85, v123
	v_mul_f32_e32 v125, v83, v125
	v_fmac_f32_e32 v123, v84, v122
	v_fmac_f32_e32 v125, v82, v124
	v_add_f32_e32 v122, v123, v125
	v_add_f32_e32 v99, v102, v122
	ds_read_b128 v[122:125], v90 offset:14336
	s_waitcnt lgkmcnt(5)
	v_mul_f32_e32 v131, v85, v131
	v_mul_f32_e32 v133, v83, v133
	v_fmac_f32_e32 v131, v84, v130
	v_fmac_f32_e32 v133, v82, v132
	v_add_f32_e32 v130, v131, v133
	v_add_f32_e32 v100, v103, v130
	ds_read_b128 v[130:133], v90 offset:18432
	s_waitcnt lgkmcnt(5)
	v_mul_f32_e32 v135, v85, v135
	v_mul_f32_e32 v137, v83, v137
	v_fmac_f32_e32 v135, v84, v134
	v_fmac_f32_e32 v137, v82, v136
	v_add_f32_e32 v134, v135, v137
	v_add_f32_e32 v82, v86, v134
	ds_read_b128 v[134:137], v90 offset:22528
	s_waitcnt lgkmcnt(5)
	v_mul_f32_e32 v139, v77, v139
	v_mul_f32_e32 v141, v75, v141
	v_fmac_f32_e32 v139, v76, v138
	v_fmac_f32_e32 v141, v74, v140
	v_add_f32_e32 v138, v139, v141
	v_add_f32_e32 v0, v0, v138
	ds_read_b128 v[138:141], v90 offset:26624
	s_waitcnt lgkmcnt(5)
	v_mul_f32_e32 v143, v77, v143
	v_mul_f32_e32 v145, v75, v145
	v_fmac_f32_e32 v143, v76, v142
	v_fmac_f32_e32 v145, v74, v144
	v_add_f32_e32 v142, v143, v145
	v_add_f32_e32 v65, v65, v142
	ds_read_b128 v[142:145], v90 offset:30720
	s_waitcnt lgkmcnt(5)
	v_mul_f32_e32 v147, v77, v147
	v_mul_f32_e32 v149, v75, v149
	v_fmac_f32_e32 v147, v76, v146
	v_fmac_f32_e32 v149, v74, v148
	v_add_f32_e32 v146, v147, v149
	v_add_f32_e32 v84, v87, v146
	ds_read_b128 v[146:149], v90 offset:34816
	s_waitcnt lgkmcnt(5)
	v_mul_f32_e32 v123, v77, v123
	v_mul_f32_e32 v125, v75, v125
	v_fmac_f32_e32 v123, v76, v122
	v_fmac_f32_e32 v125, v74, v124
	v_add_f32_e32 v122, v123, v125
	v_add_f32_e32 v85, v88, v122
	ds_read_b128 v[122:125], v90 offset:38912
	s_waitcnt lgkmcnt(5)
	v_mul_f32_e32 v131, v77, v131
	v_mul_f32_e32 v133, v75, v133
	v_fmac_f32_e32 v131, v76, v130
	v_fmac_f32_e32 v133, v74, v132
	v_add_f32_e32 v130, v131, v133
	v_add_f32_e32 v86, v89, v130
	ds_read_b128 v[130:133], v90 offset:43008
	s_waitcnt lgkmcnt(5)
	v_mul_f32_e32 v135, v77, v135
	v_mul_f32_e32 v137, v75, v137
	v_fmac_f32_e32 v135, v76, v134
	v_fmac_f32_e32 v137, v74, v136
	v_add_f32_e32 v134, v135, v137
	v_add_f32_e32 v87, v91, v134
	ds_read_b128 v[134:137], v90 offset:47104
	s_waitcnt lgkmcnt(5)
	v_mul_f32_e32 v139, v77, v139
	v_mul_f32_e32 v141, v75, v141
	v_fmac_f32_e32 v139, v76, v138
	v_fmac_f32_e32 v141, v74, v140
	v_add_f32_e32 v138, v139, v141
	v_add_f32_e32 v88, v92, v138
	ds_read_b128 v[138:141], v90 offset:51200
	s_waitcnt lgkmcnt(5)
	v_mul_f32_e32 v143, v77, v143
	v_mul_f32_e32 v145, v75, v145
	v_fmac_f32_e32 v143, v76, v142
	v_fmac_f32_e32 v145, v74, v144
	v_add_f32_e32 v142, v143, v145
	v_add_f32_e32 v89, v93, v142
	ds_read_b128 v[142:145], v90 offset:55296
	s_waitcnt lgkmcnt(5)
	v_mul_f32_e32 v147, v77, v147
	v_mul_f32_e32 v149, v75, v149
	v_fmac_f32_e32 v147, v76, v146
	v_fmac_f32_e32 v149, v74, v148
	v_add_f32_e32 v146, v147, v149
	v_add_f32_e32 v91, v94, v146
	ds_read_b128 v[146:149], v90 offset:59392
	s_waitcnt lgkmcnt(5)
	v_mul_f32_e32 v123, v77, v123
	v_mul_f32_e32 v125, v75, v125
	v_fmac_f32_e32 v123, v76, v122
	v_fmac_f32_e32 v125, v74, v124
	v_add_f32_e32 v122, v123, v125
	v_add_f32_e32 v92, v95, v122
	ds_read_b128 v[122:125], v90 offset:63488
	s_waitcnt lgkmcnt(5)
	v_mul_f32_e32 v131, v77, v131
	v_mul_f32_e32 v133, v75, v133
	v_fmac_f32_e32 v131, v76, v130
	v_fmac_f32_e32 v133, v74, v132
	v_add_f32_e32 v130, v131, v133
	v_add_f32_e32 v93, v96, v130
	ds_read_b128 v[130:133], v90 offset:3072
	s_waitcnt lgkmcnt(5)
; #define LAS __attribute__((address_space(3)))
; __device__ __forceinline__ void ph_ln1_router(const Ctx& X, CArgs a, int l, int nrows) {
;     ...
;         for (int q = 0; q < 2; ++q) {
;             unsigned cq = l4; asm volatile("" : "+v"(cq));
; #pragma unroll
;             for (int e = 0; e < 16; ++e) lgt[q][e] = 0.f;
; #pragma unroll
;             for (int j = 0; j < 4; ++j)
; #pragma unroll
;                 for (int e = 0; e < 16; ++e) { const f32x4 wr = *(const LAS f32x4*)(WR + e * 1024 + cq + 256u * j);
;                     lgt[q][e] += (v[q][j][0] * wr[0] + v[q][j][1] * wr[1]) + (v[q][j][2] * wr[2] + v[q][j][3] * wr[3]);
;                     asm volatile("" : "+v"(lgt[q][e]));
;                     if ((e & 7) == 7) __builtin_amdgcn_sched_barrier(0); }
	v_mul_f32_e32 v135, v77, v135
	v_mul_f32_e32 v137, v75, v137
	v_fmac_f32_e32 v135, v76, v134
	v_fmac_f32_e32 v137, v74, v136
	v_add_f32_e32 v134, v135, v137
	v_add_f32_e32 v94, v97, v134
	ds_read_b128 v[134:137], v90 offset:7168
	s_waitcnt lgkmcnt(5)
	v_mul_f32_e32 v139, v77, v139
	v_mul_f32_e32 v141, v75, v141
	v_fmac_f32_e32 v139, v76, v138
	v_fmac_f32_e32 v141, v74, v140
	v_add_f32_e32 v138, v139, v141
	v_add_f32_e32 v96, v98, v138
	ds_read_b128 v[138:141], v90 offset:11264
	s_waitcnt lgkmcnt(5)
	v_mul_f32_e32 v143, v77, v143
	v_mul_f32_e32 v145, v75, v145
	v_fmac_f32_e32 v143, v76, v142
	v_fmac_f32_e32 v145, v74, v144
	v_add_f32_e32 v142, v143, v145
	v_add_f32_e32 v97, v99, v142
	ds_read_b128 v[142:145], v90 offset:15360
	s_waitcnt lgkmcnt(5)
	v_mul_f32_e32 v147, v77, v147
	v_mul_f32_e32 v149, v75, v149
	v_fmac_f32_e32 v147, v76, v146
	v_fmac_f32_e32 v149, v74, v148
	v_add_f32_e32 v146, v147, v149
	v_add_f32_e32 v98, v100, v146
	ds_read_b128 v[146:149], v90 offset:19456
	s_waitcnt lgkmcnt(5)
	v_mul_f32_e32 v77, v77, v123
	v_mul_f32_e32 v75, v75, v125
	v_fmac_f32_e32 v77, v76, v122
	v_fmac_f32_e32 v75, v74, v124
	ds_read_b128 v[122:125], v90 offset:23552
	v_add_f32_e32 v74, v77, v75
	v_add_f32_e32 v99, v82, v74
	s_waitcnt lgkmcnt(5)
	v_mul_f32_e32 v131, v71, v131
	v_mul_f32_e32 v133, v69, v133
	v_fmac_f32_e32 v131, v70, v130
	v_fmac_f32_e32 v133, v68, v132
	v_add_f32_e32 v130, v131, v133
	v_add_f32_e32 v133, v0, v130
	v_mov_b32_e32 v77, v133
	ds_read_b128 v[130:133], v90 offset:27648
	s_waitcnt lgkmcnt(5)
	v_mul_f32_e32 v0, v71, v135
	v_mul_f32_e32 v74, v69, v137
	v_fmac_f32_e32 v0, v70, v134
	v_fmac_f32_e32 v74, v68, v136
	v_add_f32_e32 v0, v0, v74
	v_add_f32_e32 v134, v65, v0
	v_mov_b32_e32 v78, v134
	ds_read_b128 v[134:137], v90 offset:31744
	s_waitcnt lgkmcnt(5)
	v_mul_f32_e32 v0, v71, v139
	v_mul_f32_e32 v65, v69, v141
	v_fmac_f32_e32 v0, v70, v138
	v_fmac_f32_e32 v65, v68, v140
	ds_read_b128 v[138:141], v90 offset:35840
	v_add_f32_e32 v0, v0, v65
	v_add_f32_e32 v79, v84, v0
	s_waitcnt lgkmcnt(5)
	v_mul_f32_e32 v0, v71, v143
	v_mul_f32_e32 v65, v69, v145
	v_fmac_f32_e32 v0, v70, v142
	v_fmac_f32_e32 v65, v68, v144
	ds_read_b128 v[142:145], v90 offset:39936
	v_add_f32_e32 v0, v0, v65
	v_add_f32_e32 v74, v85, v0
	s_waitcnt lgkmcnt(5)
	v_mul_f32_e32 v0, v71, v147
	v_mul_f32_e32 v65, v69, v149
	v_fmac_f32_e32 v0, v70, v146
	v_fmac_f32_e32 v65, v68, v148
	ds_read_b128 v[146:149], v90 offset:44032
	v_add_f32_e32 v0, v0, v65
	v_add_f32_e32 v75, v86, v0
	s_waitcnt lgkmcnt(5)
	v_mul_f32_e32 v0, v71, v123
	v_mul_f32_e32 v65, v69, v125
	v_fmac_f32_e32 v0, v70, v122
	v_fmac_f32_e32 v65, v68, v124
	ds_read_b128 v[122:125], v90 offset:48128
	v_add_f32_e32 v0, v0, v65
	v_add_f32_e32 v76, v87, v0
	s_waitcnt lgkmcnt(5)
	v_mul_f32_e32 v0, v71, v131
	v_mul_f32_e32 v65, v69, v133
	v_fmac_f32_e32 v0, v70, v130
	v_fmac_f32_e32 v65, v68, v132
	ds_read_b128 v[130:133], v90 offset:52224
	v_add_f32_e32 v0, v0, v65
	v_add_f32_e32 v0, v88, v0
	s_waitcnt lgkmcnt(5)
	v_mul_f32_e32 v65, v71, v135
	v_mul_f32_e32 v135, v69, v137
	v_fmac_f32_e32 v65, v70, v134
	v_fmac_f32_e32 v135, v68, v136
	v_add_f32_e32 v65, v65, v135
	ds_read_b128 v[134:137], v90 offset:56320
	v_add_f32_e32 v65, v89, v65
	s_waitcnt lgkmcnt(5)
	v_mul_f32_e32 v139, v71, v139
	v_mul_f32_e32 v141, v69, v141
	v_fmac_f32_e32 v139, v70, v138
	v_fmac_f32_e32 v141, v68, v140
	v_add_f32_e32 v138, v139, v141
	v_add_f32_e32 v84, v91, v138
	ds_read_b128 v[138:141], v90 offset:60416
	s_waitcnt lgkmcnt(5)
	v_mul_f32_e32 v143, v71, v143
	v_mul_f32_e32 v145, v69, v145
	v_fmac_f32_e32 v143, v70, v142
	v_fmac_f32_e32 v145, v68, v144
	v_add_f32_e32 v142, v143, v145
	v_add_f32_e32 v85, v92, v142
	ds_read_b128 v[142:145], v90 offset:64512
	s_waitcnt lgkmcnt(5)
	v_mul_f32_e32 v147, v71, v147
	v_mul_f32_e32 v149, v69, v149
	v_fmac_f32_e32 v147, v70, v146
	v_fmac_f32_e32 v149, v68, v148
	v_add_f32_e32 v146, v147, v149
	v_add_f32_e32 v86, v93, v146
	s_waitcnt lgkmcnt(4)
	v_mul_f32_e32 v123, v71, v123
	v_mul_f32_e32 v125, v69, v125
	v_fmac_f32_e32 v123, v70, v122
	v_fmac_f32_e32 v125, v68, v124
	v_add_f32_e32 v122, v123, v125
	v_add_f32_e32 v123, v94, v122
	v_mov_b32_e32 v81, v123
	s_waitcnt lgkmcnt(3)
	v_mul_f32_e32 v80, v71, v131
	v_mul_f32_e32 v82, v69, v133
	v_fmac_f32_e32 v80, v70, v130
	v_fmac_f32_e32 v82, v68, v132
	v_add_f32_e32 v80, v80, v82
	v_add_f32_e32 v82, v96, v80
	s_waitcnt lgkmcnt(2)
	v_mul_f32_e32 v80, v71, v135
	v_mul_f32_e32 v83, v69, v137
	v_fmac_f32_e32 v80, v70, v134
	v_fmac_f32_e32 v83, v68, v136
	v_add_f32_e32 v80, v80, v83
	v_add_f32_e32 v83, v97, v80
	s_waitcnt lgkmcnt(1)
	v_mul_f32_e32 v80, v71, v139
	v_mul_f32_e32 v87, v69, v141
	v_fmac_f32_e32 v80, v70, v138
	v_fmac_f32_e32 v87, v68, v140
	v_add_f32_e32 v80, v80, v87
	v_add_f32_e32 v80, v98, v80
	s_waitcnt lgkmcnt(0)
	v_mul_f32_e32 v71, v71, v143
	v_mul_f32_e32 v69, v69, v145
	v_fmac_f32_e32 v71, v70, v142
	v_fmac_f32_e32 v69, v68, v144
	v_add_f32_e32 v68, v71, v69
	v_add_f32_e32 v68, v99, v68
	s_nop 0
	v_lshl_add_u32 v64, v64, 2, 0
	s_waitcnt lgkmcnt(0)
	ds_read_b128 v[146:149], v64
	ds_read_b128 v[122:125], v64 offset:4096
	ds_read_b128 v[130:133], v64 offset:8192
	ds_read_b128 v[134:137], v64 offset:12288
	ds_read_b128 v[138:141], v64 offset:16384
	ds_read_b128 v[142:145], v64 offset:20480
	s_waitcnt lgkmcnt(5)
	v_mul_f32_e32 v69, v73, v147
	v_mul_f32_e32 v70, v67, v149
	v_fmac_f32_e32 v69, v72, v146
	v_fmac_f32_e32 v70, v66, v148
	ds_read_b128 v[146:149], v64 offset:24576
	v_add_f32_e32 v69, v69, v70
	v_add_f32_e32 v69, 0, v69
	s_waitcnt lgkmcnt(5)
; #define LAS __attribute__((address_space(3)))
; __device__ __forceinline__ void ph_ln1_router(const Ctx& X, CArgs a, int l, int nrows) {
;     ...
;         for (int q = 0; q < 2; ++q) {
;             unsigned cq = l4; asm volatile("" : "+v"(cq));
; #pragma unroll
;             for (int e = 0; e < 16; ++e) lgt[q][e] = 0.f;
; #pragma unroll
;             for (int j = 0; j < 4; ++j)
; #pragma unroll
;                 for (int e = 0; e < 16; ++e) { const f32x4 wr = *(const LAS f32x4*)(WR + e * 1024 + cq + 256u * j);
;                     lgt[q][e] += (v[q][j][0] * wr[0] + v[q][j][1] * wr[1]) + (v[q][j][2] * wr[2] + v[q][j][3] * wr[3]);
;                     asm volatile("" : "+v"(lgt[q][e]));
;                     if ((e & 7) == 7) __builtin_amdgcn_sched_barrier(0); }
	v_mul_f32_e32 v70, v73, v123
	v_mul_f32_e32 v71, v67, v125
	v_fmac_f32_e32 v70, v72, v122
	v_fmac_f32_e32 v71, v66, v124
	ds_read_b128 v[122:125], v64 offset:28672
	v_add_f32_e32 v70, v70, v71
	v_add_f32_e32 v87, 0, v70
	s_waitcnt lgkmcnt(5)
	v_mul_f32_e32 v70, v73, v131
	v_mul_f32_e32 v71, v67, v133
	v_fmac_f32_e32 v70, v72, v130
	v_fmac_f32_e32 v71, v66, v132
	ds_read_b128 v[130:133], v64 offset:32768
	v_add_f32_e32 v70, v70, v71
	v_add_f32_e32 v92, 0, v70
	s_waitcnt lgkmcnt(5)
	v_mul_f32_e32 v70, v73, v135
	v_mul_f32_e32 v71, v67, v137
	v_fmac_f32_e32 v70, v72, v134
	v_fmac_f32_e32 v71, v66, v136
	ds_read_b128 v[134:137], v64 offset:36864
	v_add_f32_e32 v70, v70, v71
	v_add_f32_e32 v93, 0, v70
	s_waitcnt lgkmcnt(5)
	v_mul_f32_e32 v70, v73, v139
	v_mul_f32_e32 v71, v67, v141
	v_fmac_f32_e32 v70, v72, v138
	v_fmac_f32_e32 v71, v66, v140
	ds_read_b128 v[138:141], v64 offset:40960
	v_add_f32_e32 v70, v70, v71
	v_add_f32_e32 v94, 0, v70
	s_waitcnt lgkmcnt(5)
	v_mul_f32_e32 v70, v73, v143
	v_mul_f32_e32 v71, v67, v145
	v_fmac_f32_e32 v70, v72, v142
	v_fmac_f32_e32 v71, v66, v144
	ds_read_b128 v[142:145], v64 offset:45056
	v_add_f32_e32 v70, v70, v71
	v_add_f32_e32 v95, 0, v70
	s_waitcnt lgkmcnt(5)
	v_mul_f32_e32 v70, v73, v147
	v_mul_f32_e32 v71, v67, v149
	v_fmac_f32_e32 v70, v72, v146
	v_fmac_f32_e32 v71, v66, v148
	ds_read_b128 v[146:149], v64 offset:49152
	v_add_f32_e32 v70, v70, v71
	v_add_f32_e32 v96, 0, v70
	s_waitcnt lgkmcnt(5)
	v_mul_f32_e32 v70, v73, v123
	v_mul_f32_e32 v71, v67, v125
	v_fmac_f32_e32 v70, v72, v122
	v_fmac_f32_e32 v71, v66, v124
	ds_read_b128 v[122:125], v64 offset:53248
	v_add_f32_e32 v70, v70, v71
	v_add_f32_e32 v97, 0, v70
	s_waitcnt lgkmcnt(5)
	v_mul_f32_e32 v70, v73, v131
	v_mul_f32_e32 v71, v67, v133
	v_fmac_f32_e32 v70, v72, v130
	v_fmac_f32_e32 v71, v66, v132
	ds_read_b128 v[130:133], v64 offset:57344
	v_add_f32_e32 v70, v70, v71
	v_add_f32_e32 v98, 0, v70
	s_waitcnt lgkmcnt(5)
	v_mul_f32_e32 v70, v73, v135
	v_mul_f32_e32 v71, v67, v137
	v_fmac_f32_e32 v70, v72, v134
	v_fmac_f32_e32 v71, v66, v136
	ds_read_b128 v[134:137], v64 offset:61440
	v_add_f32_e32 v70, v70, v71
	v_add_f32_e32 v99, 0, v70
	s_waitcnt lgkmcnt(5)
	v_mul_f32_e32 v70, v73, v139
	v_mul_f32_e32 v71, v67, v141
	v_fmac_f32_e32 v70, v72, v138
	v_fmac_f32_e32 v71, v66, v140
	ds_read_b128 v[138:141], v64 offset:1024
	v_add_f32_e32 v70, v70, v71
	v_add_f32_e32 v100, 0, v70
	s_waitcnt lgkmcnt(5)
	v_mul_f32_e32 v70, v73, v143
	v_mul_f32_e32 v71, v67, v145
	v_fmac_f32_e32 v70, v72, v142
	v_fmac_f32_e32 v71, v66, v144
	ds_read_b128 v[142:145], v64 offset:5120
	v_add_f32_e32 v70, v70, v71
	v_add_f32_e32 v101, 0, v70
	s_waitcnt lgkmcnt(5)
	v_mul_f32_e32 v70, v73, v147
	v_mul_f32_e32 v71, v67, v149
	v_fmac_f32_e32 v70, v72, v146
	v_fmac_f32_e32 v71, v66, v148
	ds_read_b128 v[146:149], v64 offset:9216
	v_add_f32_e32 v70, v70, v71
	v_add_f32_e32 v102, 0, v70
	s_waitcnt lgkmcnt(5)
	v_mul_f32_e32 v70, v73, v123
	v_mul_f32_e32 v71, v67, v125
	v_fmac_f32_e32 v70, v72, v122
	v_fmac_f32_e32 v71, v66, v124
	ds_read_b128 v[122:125], v64 offset:13312
	v_add_f32_e32 v70, v70, v71
	v_add_f32_e32 v103, 0, v70
	s_waitcnt lgkmcnt(5)
	v_mul_f32_e32 v70, v73, v131
	v_mul_f32_e32 v71, v67, v133
	v_fmac_f32_e32 v70, v72, v130
	v_fmac_f32_e32 v71, v66, v132
	ds_read_b128 v[130:133], v64 offset:17408
	v_add_f32_e32 v70, v70, v71
	v_add_f32_e32 v104, 0, v70
	s_waitcnt lgkmcnt(5)
	v_mul_f32_e32 v70, v73, v135
	v_mul_f32_e32 v67, v67, v137
	v_fmac_f32_e32 v70, v72, v134
	v_fmac_f32_e32 v67, v66, v136
	ds_read_b128 v[134:137], v64 offset:21504
	v_add_f32_e32 v66, v70, v67
	v_add_f32_e32 v66, 0, v66
	s_waitcnt lgkmcnt(5)
	v_mul_f32_e32 v67, v45, v139
	v_mul_f32_e32 v139, v43, v141
	v_fmac_f32_e32 v67, v44, v138
	v_fmac_f32_e32 v139, v42, v140
	v_add_f32_e32 v67, v67, v139
	v_add_f32_e32 v67, v69, v67
	s_waitcnt lgkmcnt(4)
	v_mul_f32_e32 v69, v45, v143
	v_mul_f32_e32 v143, v43, v145
	v_fmac_f32_e32 v69, v44, v142
	v_fmac_f32_e32 v143, v42, v144
	v_add_f32_e32 v69, v69, v143
	v_add_f32_e32 v69, v87, v69
	s_waitcnt lgkmcnt(3)
	v_mul_f32_e32 v147, v45, v147
	v_mul_f32_e32 v149, v43, v149
	v_fmac_f32_e32 v147, v44, v146
	v_fmac_f32_e32 v149, v42, v148
	v_add_f32_e32 v146, v147, v149
	v_add_f32_e32 v87, v92, v146
	s_waitcnt lgkmcnt(2)
	v_mul_f32_e32 v123, v45, v123
	v_mul_f32_e32 v125, v43, v125
	v_fmac_f32_e32 v123, v44, v122
	v_fmac_f32_e32 v125, v42, v124
	v_add_f32_e32 v122, v123, v125
	v_add_f32_e32 v88, v93, v122
	s_waitcnt lgkmcnt(1)
	v_mul_f32_e32 v131, v45, v131
	v_mul_f32_e32 v133, v43, v133
	v_fmac_f32_e32 v131, v44, v130
	v_fmac_f32_e32 v133, v42, v132
	v_add_f32_e32 v130, v131, v133
	v_add_f32_e32 v89, v94, v130
	s_waitcnt lgkmcnt(0)
	v_mul_f32_e32 v135, v45, v135
	v_mul_f32_e32 v137, v43, v137
	v_fmac_f32_e32 v135, v44, v134
	v_fmac_f32_e32 v137, v42, v136
	v_add_f32_e32 v134, v135, v137
	v_add_f32_e32 v90, v95, v134
	s_waitcnt lgkmcnt(0)
	ds_read_b128 v[138:141], v64 offset:25600
	ds_read_b128 v[142:145], v64 offset:29696
	ds_read_b128 v[146:149], v64 offset:33792
	ds_read_b128 v[122:125], v64 offset:37888
	ds_read_b128 v[130:133], v64 offset:41984
	ds_read_b128 v[134:137], v64 offset:46080
	s_waitcnt lgkmcnt(5)
	v_mul_f32_e32 v139, v45, v139
	v_mul_f32_e32 v141, v43, v141
	v_fmac_f32_e32 v139, v44, v138
	v_fmac_f32_e32 v141, v42, v140
	v_add_f32_e32 v138, v139, v141
	v_add_f32_e32 v91, v96, v138
	ds_read_b128 v[138:141], v64 offset:50176
	s_waitcnt lgkmcnt(5)
	v_mul_f32_e32 v143, v45, v143
	v_mul_f32_e32 v145, v43, v145
	v_fmac_f32_e32 v143, v44, v142
	v_fmac_f32_e32 v145, v42, v144
	v_add_f32_e32 v142, v143, v145
	v_add_f32_e32 v92, v97, v142
	ds_read_b128 v[142:145], v64 offset:54272
	s_waitcnt lgkmcnt(5)
; #define LAS __attribute__((address_space(3)))
; __device__ __forceinline__ void ph_ln1_router(const Ctx& X, CArgs a, int l, int nrows) {
;     ...
; #pragma unroll
;             for (int j = 0; j < 4; ++j)
; #pragma unroll
;                 for (int e = 0; e < 16; ++e) { const f32x4 wr = *(const LAS f32x4*)(WR + e * 1024 + cq + 256u * j);
;                     lgt[q][e] += (v[q][j][0] * wr[0] + v[q][j][1] * wr[1]) + (v[q][j][2] * wr[2] + v[q][j][3] * wr[3]);
;                     asm volatile("" : "+v"(lgt[q][e]));
;                     if ((e & 7) == 7) __builtin_amdgcn_sched_barrier(0); }
	v_mul_f32_e32 v147, v45, v147
	v_mul_f32_e32 v149, v43, v149
	v_fmac_f32_e32 v147, v44, v146
	v_fmac_f32_e32 v149, v42, v148
	v_add_f32_e32 v146, v147, v149
	v_add_f32_e32 v93, v98, v146
	ds_read_b128 v[146:149], v64 offset:58368
	s_waitcnt lgkmcnt(5)
	v_mul_f32_e32 v123, v45, v123
	v_mul_f32_e32 v125, v43, v125
	v_fmac_f32_e32 v123, v44, v122
	v_fmac_f32_e32 v125, v42, v124
	v_add_f32_e32 v122, v123, v125
	v_add_f32_e32 v94, v99, v122
	ds_read_b128 v[122:125], v64 offset:62464
	s_waitcnt lgkmcnt(5)
	v_mul_f32_e32 v131, v45, v131
	v_mul_f32_e32 v133, v43, v133
	v_fmac_f32_e32 v131, v44, v130
	v_fmac_f32_e32 v133, v42, v132
	v_add_f32_e32 v130, v131, v133
	v_add_f32_e32 v95, v100, v130
	ds_read_b128 v[130:133], v64 offset:2048
	s_waitcnt lgkmcnt(5)
	v_mul_f32_e32 v135, v45, v135
	v_mul_f32_e32 v137, v43, v137
	v_fmac_f32_e32 v135, v44, v134
	v_fmac_f32_e32 v137, v42, v136
	v_add_f32_e32 v134, v135, v137
	v_add_f32_e32 v96, v101, v134
	ds_read_b128 v[134:137], v64 offset:6144
	s_waitcnt lgkmcnt(5)
	v_mul_f32_e32 v139, v45, v139
	v_mul_f32_e32 v141, v43, v141
	v_fmac_f32_e32 v139, v44, v138
	v_fmac_f32_e32 v141, v42, v140
	v_add_f32_e32 v138, v139, v141
	v_add_f32_e32 v97, v102, v138
	ds_read_b128 v[138:141], v64 offset:10240
	s_waitcnt lgkmcnt(5)
	v_mul_f32_e32 v143, v45, v143
	v_mul_f32_e32 v145, v43, v145
	v_fmac_f32_e32 v143, v44, v142
	v_fmac_f32_e32 v145, v42, v144
	v_add_f32_e32 v142, v143, v145
	v_add_f32_e32 v98, v103, v142
	ds_read_b128 v[142:145], v64 offset:14336
	s_waitcnt lgkmcnt(5)
	v_mul_f32_e32 v147, v45, v147
	v_mul_f32_e32 v149, v43, v149
	v_fmac_f32_e32 v147, v44, v146
	v_fmac_f32_e32 v149, v42, v148
	v_add_f32_e32 v146, v147, v149
	v_add_f32_e32 v99, v104, v146
	ds_read_b128 v[146:149], v64 offset:18432
	s_waitcnt lgkmcnt(5)
	v_mul_f32_e32 v45, v45, v123
	v_mul_f32_e32 v43, v43, v125
	v_fmac_f32_e32 v45, v44, v122
	v_fmac_f32_e32 v43, v42, v124
	ds_read_b128 v[122:125], v64 offset:22528
	v_add_f32_e32 v42, v45, v43
	v_add_f32_e32 v66, v66, v42
	s_waitcnt lgkmcnt(5)
	v_mul_f32_e32 v131, v41, v131
	v_mul_f32_e32 v133, v39, v133
	v_fmac_f32_e32 v131, v40, v130
	v_fmac_f32_e32 v133, v38, v132
	v_add_f32_e32 v130, v131, v133
	v_add_f32_e32 v67, v67, v130
	ds_read_b128 v[130:133], v64 offset:26624
	s_waitcnt lgkmcnt(5)
	v_mul_f32_e32 v135, v41, v135
	v_mul_f32_e32 v137, v39, v137
	v_fmac_f32_e32 v135, v40, v134
	v_fmac_f32_e32 v137, v38, v136
	v_add_f32_e32 v134, v135, v137
	v_add_f32_e32 v69, v69, v134
	ds_read_b128 v[134:137], v64 offset:30720
	s_waitcnt lgkmcnt(5)
	v_mul_f32_e32 v139, v41, v139
	v_mul_f32_e32 v141, v39, v141
	v_fmac_f32_e32 v139, v40, v138
	v_fmac_f32_e32 v141, v38, v140
	v_add_f32_e32 v138, v139, v141
	v_add_f32_e32 v70, v87, v138
	s_waitcnt lgkmcnt(4)
	v_mul_f32_e32 v143, v41, v143
	v_mul_f32_e32 v145, v39, v145
	v_fmac_f32_e32 v143, v40, v142
	v_fmac_f32_e32 v145, v38, v144
	v_add_f32_e32 v142, v143, v145
	v_add_f32_e32 v71, v88, v142
	s_waitcnt lgkmcnt(3)
	v_mul_f32_e32 v147, v41, v147
	v_mul_f32_e32 v149, v39, v149
	v_fmac_f32_e32 v147, v40, v146
	v_fmac_f32_e32 v149, v38, v148
	v_add_f32_e32 v146, v147, v149
	v_add_f32_e32 v87, v89, v146
	s_waitcnt lgkmcnt(2)
	v_mul_f32_e32 v123, v41, v123
	v_mul_f32_e32 v125, v39, v125
	v_fmac_f32_e32 v123, v40, v122
	v_fmac_f32_e32 v125, v38, v124
	v_add_f32_e32 v122, v123, v125
	v_add_f32_e32 v88, v90, v122
	s_waitcnt lgkmcnt(1)
	v_mul_f32_e32 v131, v41, v131
	v_mul_f32_e32 v133, v39, v133
	v_fmac_f32_e32 v131, v40, v130
	v_fmac_f32_e32 v133, v38, v132
	v_add_f32_e32 v130, v131, v133
	v_add_f32_e32 v89, v91, v130
	s_waitcnt lgkmcnt(0)
	v_mul_f32_e32 v135, v41, v135
	v_mul_f32_e32 v137, v39, v137
	v_fmac_f32_e32 v135, v40, v134
	v_fmac_f32_e32 v137, v38, v136
	v_add_f32_e32 v134, v135, v137
	v_add_f32_e32 v90, v92, v134
	s_waitcnt lgkmcnt(0)
	ds_read_b128 v[138:141], v64 offset:34816
	ds_read_b128 v[142:145], v64 offset:38912
	ds_read_b128 v[146:149], v64 offset:43008
	ds_read_b128 v[122:125], v64 offset:47104
	ds_read_b128 v[130:133], v64 offset:51200
	ds_read_b128 v[134:137], v64 offset:55296
	s_waitcnt lgkmcnt(5)
	v_mul_f32_e32 v139, v41, v139
	v_mul_f32_e32 v141, v39, v141
	v_fmac_f32_e32 v139, v40, v138
	v_fmac_f32_e32 v141, v38, v140
	v_add_f32_e32 v138, v139, v141
	v_add_f32_e32 v91, v93, v138
	ds_read_b128 v[138:141], v64 offset:59392
	s_waitcnt lgkmcnt(5)
	v_mul_f32_e32 v143, v41, v143
	v_mul_f32_e32 v145, v39, v145
	v_fmac_f32_e32 v143, v40, v142
	v_fmac_f32_e32 v145, v38, v144
	v_add_f32_e32 v142, v143, v145
	v_add_f32_e32 v92, v94, v142
	ds_read_b128 v[142:145], v64 offset:63488
	s_waitcnt lgkmcnt(5)
	v_mul_f32_e32 v147, v41, v147
	v_mul_f32_e32 v149, v39, v149
	v_fmac_f32_e32 v147, v40, v146
	v_fmac_f32_e32 v149, v38, v148
	v_add_f32_e32 v146, v147, v149
	v_add_f32_e32 v93, v95, v146
	ds_read_b128 v[146:149], v64 offset:3072
	s_waitcnt lgkmcnt(5)
	v_mul_f32_e32 v123, v41, v123
	v_mul_f32_e32 v125, v39, v125
	v_fmac_f32_e32 v123, v40, v122
	v_fmac_f32_e32 v125, v38, v124
	v_add_f32_e32 v122, v123, v125
	v_add_f32_e32 v94, v96, v122
	ds_read_b128 v[122:125], v64 offset:7168
	s_waitcnt lgkmcnt(5)
	v_mul_f32_e32 v131, v41, v131
	v_mul_f32_e32 v133, v39, v133
	v_fmac_f32_e32 v131, v40, v130
	v_fmac_f32_e32 v133, v38, v132
	v_add_f32_e32 v130, v131, v133
	v_add_f32_e32 v95, v97, v130
	ds_read_b128 v[130:133], v64 offset:11264
	s_waitcnt lgkmcnt(5)
	v_mul_f32_e32 v135, v41, v135
	v_mul_f32_e32 v137, v39, v137
	v_fmac_f32_e32 v135, v40, v134
	v_fmac_f32_e32 v137, v38, v136
	v_add_f32_e32 v134, v135, v137
	v_add_f32_e32 v96, v98, v134
	ds_read_b128 v[134:137], v64 offset:15360
	s_waitcnt lgkmcnt(5)
; #define LAS __attribute__((address_space(3)))
; __device__ __forceinline__ void ph_ln1_router(const Ctx& X, CArgs a, int l, int nrows) {
;     ...
; #pragma unroll
;             for (int j = 0; j < 4; ++j)
; #pragma unroll
;                 for (int e = 0; e < 16; ++e) { const f32x4 wr = *(const LAS f32x4*)(WR + e * 1024 + cq + 256u * j);
;                     lgt[q][e] += (v[q][j][0] * wr[0] + v[q][j][1] * wr[1]) + (v[q][j][2] * wr[2] + v[q][j][3] * wr[3]);
;                     asm volatile("" : "+v"(lgt[q][e]));
;                     if ((e & 7) == 7) __builtin_amdgcn_sched_barrier(0); }
;         }
; #pragma unroll
;         for (int q = 0; q < 2; ++q) {
;             float k8[8], k4[4], k2[2], k1;
;             { const bool hi = (X.lane & 32) != 0;
; #pragma unroll
;               for (int e = 0; e < 8; ++e) { const float send = hi ? lgt[q][e] : lgt[q][e + 8], keep = hi ? lgt[q][e + 8] : lgt[q][e]; k8[e] = keep + __shfl_xor(send, 32); } }
	v_mul_f32_e32 v139, v41, v139
	v_mul_f32_e32 v141, v39, v141
	v_fmac_f32_e32 v139, v40, v138
	v_fmac_f32_e32 v141, v38, v140
	v_add_f32_e32 v138, v139, v141
	v_add_f32_e32 v97, v99, v138
	ds_read_b128 v[138:141], v64 offset:19456
	s_waitcnt lgkmcnt(5)
	v_mul_f32_e32 v41, v41, v143
	v_mul_f32_e32 v39, v39, v145
	v_fmac_f32_e32 v41, v40, v142
	v_fmac_f32_e32 v39, v38, v144
	ds_read_b128 v[142:145], v64 offset:23552
	v_add_f32_e32 v38, v41, v39
	v_add_f32_e32 v98, v66, v38
	s_waitcnt lgkmcnt(5)
	v_mul_f32_e32 v147, v37, v147
	v_mul_f32_e32 v149, v35, v149
	v_fmac_f32_e32 v147, v36, v146
	v_fmac_f32_e32 v149, v34, v148
	v_add_f32_e32 v146, v147, v149
	v_add_f32_e32 v43, v67, v146
	ds_read_b128 v[146:149], v64 offset:27648
	s_waitcnt lgkmcnt(5)
	v_mul_f32_e32 v123, v37, v123
	v_mul_f32_e32 v125, v35, v125
	v_fmac_f32_e32 v123, v36, v122
	v_fmac_f32_e32 v125, v34, v124
	v_add_f32_e32 v122, v123, v125
	v_add_f32_e32 v44, v69, v122
	ds_read_b128 v[122:125], v64 offset:31744
	s_waitcnt lgkmcnt(5)
	v_mul_f32_e32 v131, v37, v131
	v_mul_f32_e32 v133, v35, v133
	v_fmac_f32_e32 v131, v36, v130
	v_fmac_f32_e32 v133, v34, v132
	v_add_f32_e32 v130, v131, v133
	v_add_f32_e32 v45, v70, v130
	ds_read_b128 v[130:133], v64 offset:35840
	s_waitcnt lgkmcnt(5)
	v_mul_f32_e32 v135, v37, v135
	v_mul_f32_e32 v137, v35, v137
	v_fmac_f32_e32 v135, v36, v134
	v_fmac_f32_e32 v137, v34, v136
	v_add_f32_e32 v134, v135, v137
	v_add_f32_e32 v136, v71, v134
	v_mov_b32_e32 v40, v136
	ds_read_b128 v[134:137], v64 offset:39936
	s_waitcnt lgkmcnt(5)
	v_mul_f32_e32 v38, v37, v139
	v_mul_f32_e32 v39, v35, v141
	v_fmac_f32_e32 v38, v36, v138
	v_fmac_f32_e32 v39, v34, v140
	ds_read_b128 v[138:141], v64 offset:44032
	v_add_f32_e32 v38, v38, v39
	v_add_f32_e32 v41, v87, v38
	s_waitcnt lgkmcnt(5)
	v_mul_f32_e32 v38, v37, v143
	v_mul_f32_e32 v39, v35, v145
	v_fmac_f32_e32 v38, v36, v142
	v_fmac_f32_e32 v39, v34, v144
	ds_read_b128 v[142:145], v64 offset:48128
	v_add_f32_e32 v38, v38, v39
	v_add_f32_e32 v42, v88, v38
	s_waitcnt lgkmcnt(5)
	v_mul_f32_e32 v38, v37, v147
	v_mul_f32_e32 v39, v35, v149
	v_fmac_f32_e32 v38, v36, v146
	v_fmac_f32_e32 v39, v34, v148
	ds_read_b128 v[146:149], v64 offset:52224
	v_add_f32_e32 v38, v38, v39
	v_add_f32_e32 v38, v89, v38
	s_waitcnt lgkmcnt(5)
	v_mul_f32_e32 v39, v37, v123
	v_mul_f32_e32 v66, v35, v125
	v_fmac_f32_e32 v39, v36, v122
	v_fmac_f32_e32 v66, v34, v124
	ds_read_b128 v[122:125], v64 offset:56320
	v_add_f32_e32 v39, v39, v66
	v_add_f32_e32 v39, v90, v39
	s_waitcnt lgkmcnt(5)
	v_mul_f32_e32 v66, v37, v131
	v_mul_f32_e32 v67, v35, v133
	v_fmac_f32_e32 v66, v36, v130
	v_fmac_f32_e32 v67, v34, v132
	v_add_f32_e32 v66, v66, v67
	v_add_f32_e32 v131, v91, v66
	v_mov_b32_e32 v71, v131
	ds_read_b128 v[130:133], v64 offset:60416
	s_waitcnt lgkmcnt(5)
	v_mul_f32_e32 v66, v37, v135
	v_mul_f32_e32 v67, v35, v137
	v_fmac_f32_e32 v66, v36, v134
	v_fmac_f32_e32 v67, v34, v136
	v_add_f32_e32 v66, v66, v67
	v_add_f32_e32 v72, v92, v66
	s_waitcnt lgkmcnt(4)
	v_mul_f32_e32 v66, v37, v139
	v_mul_f32_e32 v67, v35, v141
	v_fmac_f32_e32 v66, v36, v138
	v_fmac_f32_e32 v67, v34, v140
	v_add_f32_e32 v66, v66, v67
	v_add_f32_e32 v73, v93, v66
	s_waitcnt lgkmcnt(3)
	v_mul_f32_e32 v66, v37, v143
	v_mul_f32_e32 v67, v35, v145
	v_fmac_f32_e32 v66, v36, v142
	v_fmac_f32_e32 v67, v34, v144
	v_add_f32_e32 v66, v66, v67
	v_add_f32_e32 v67, v94, v66
	s_waitcnt lgkmcnt(2)
	v_mul_f32_e32 v66, v37, v147
	v_mul_f32_e32 v69, v35, v149
	v_fmac_f32_e32 v66, v36, v146
	v_fmac_f32_e32 v69, v34, v148
	v_add_f32_e32 v66, v66, v69
	v_add_f32_e32 v69, v95, v66
	s_waitcnt lgkmcnt(1)
	v_mul_f32_e32 v66, v37, v123
	v_mul_f32_e32 v70, v35, v125
	v_fmac_f32_e32 v66, v36, v122
	v_fmac_f32_e32 v70, v34, v124
	v_add_f32_e32 v66, v66, v70
	v_add_f32_e32 v70, v96, v66
	s_waitcnt lgkmcnt(0)
	v_mul_f32_e32 v66, v37, v131
	v_mul_f32_e32 v87, v35, v133
	v_fmac_f32_e32 v66, v36, v130
	v_fmac_f32_e32 v87, v34, v132
	v_add_f32_e32 v66, v66, v87
	v_add_f32_e32 v66, v97, v66
	ds_read_b128 v[88:91], v64 offset:64512
	s_waitcnt lgkmcnt(0)
	v_mul_f32_e32 v37, v37, v89
	v_mul_f32_e32 v35, v35, v91
	v_fmac_f32_e32 v37, v36, v88
	v_fmac_f32_e32 v35, v34, v90
	v_add_f32_e32 v34, v37, v35
	v_add_f32_e32 v34, v98, v34
	v_cndmask_b32_e64 v35, v77, v84, s[4:5]
	ds_bpermute_b32 v35, v247, v35
	v_cndmask_b32_e64 v36, v84, v77, s[4:5]
	v_cndmask_b32_e64 v37, v85, v78, s[4:5]
	v_cndmask_b32_e64 v64, v86, v79, s[4:5]
	s_mov_b32 s25, 0x3fb8aa3b
	s_waitcnt lgkmcnt(0)
; __device__ __forceinline__ void ph_ln1_router(const Ctx& X, CArgs a, int l, int nrows) {
;     ...
;         for (int q = 0; q < 2; ++q) {
;             float k8[8], k4[4], k2[2], k1;
;             { const bool hi = (X.lane & 32) != 0;
; #pragma unroll
;               for (int e = 0; e < 8; ++e) { const float send = hi ? lgt[q][e] : lgt[q][e + 8], keep = hi ? lgt[q][e + 8] : lgt[q][e]; k8[e] = keep + __shfl_xor(send, 32); } }
;             { const bool hi = (X.lane & 16) != 0;
; #pragma unroll
;               for (int e = 0; e < 4; ++e) { const float send = hi ? k8[e] : k8[e + 4], keep = hi ? k8[e + 4] : k8[e]; k4[e] = keep + __shfl_xor(send, 16); } }
;             { const bool hi = (X.lane & 8) != 0;
; #pragma unroll
;               for (int e = 0; e < 2; ++e) { const float send = hi ? k4[e] : k4[e + 2], keep = hi ? k4[e + 2] : k4[e]; k2[e] = keep + __shfl_xor(send, 8); } }
;             { const bool hi = (X.lane & 4) != 0; const float send = hi ? k2[0] : k2[1], keep = hi ? k2[1] : k2[0]; k1 = keep + __shfl_xor(send, 4); }
;             k1 += __shfl_xor(k1, 2); k1 += __shfl_xor(k1, 1);
;             float mx = k1;
;             mx = fmaxf(mx, __shfl_xor(mx, 32)); mx = fmaxf(mx, __shfl_xor(mx, 16)); mx = fmaxf(mx, __shfl_xor(mx, 8)); mx = fmaxf(mx, __shfl_xor(mx, 4));
;             const float ex = expf(k1 - mx); float den = ex;
;             den += __shfl_xor(den, 32); den += __shfl_xor(den, 16); den += __shfl_xor(den, 8); den += __shfl_xor(den, 4);
;             const int eidx = ((X.lane >> 5) & 1) * 8 + ((X.lane >> 4) & 1) * 4 + ((X.lane >> 3) & 1) * 2 + ((X.lane >> 2) & 1);
;             if ((X.lane & 3) == 0) AFF[(size_t)(r0 + q) * 16 + eidx] = ex / den;
	v_add_f32_e32 v35, v36, v35
	v_cndmask_b32_e64 v36, v78, v85, s[4:5]
	ds_bpermute_b32 v36, v247, v36
	s_waitcnt lgkmcnt(0)
	v_add_f32_e32 v36, v37, v36
	v_cndmask_b32_e64 v37, v79, v86, s[4:5]
	ds_bpermute_b32 v37, v247, v37
	s_waitcnt lgkmcnt(0)
	v_add_f32_e32 v37, v64, v37
	v_cndmask_b32_e64 v64, v74, v81, s[4:5]
	ds_bpermute_b32 v64, v247, v64
	v_cndmask_b32_e64 v74, v81, v74, s[4:5]
	s_waitcnt lgkmcnt(0)
	v_add_f32_e32 v64, v74, v64
	v_cndmask_b32_e64 v74, v75, v82, s[4:5]
	ds_bpermute_b32 v74, v247, v74
	v_cndmask_b32_e64 v75, v82, v75, s[4:5]
	s_waitcnt lgkmcnt(0)
	v_add_f32_e32 v74, v75, v74
	v_cndmask_b32_e64 v75, v76, v83, s[4:5]
	ds_bpermute_b32 v75, v247, v75
	v_cndmask_b32_e64 v76, v83, v76, s[4:5]
	s_waitcnt lgkmcnt(0)
	v_add_f32_e32 v75, v76, v75
	v_cndmask_b32_e64 v76, v0, v80, s[4:5]
	ds_bpermute_b32 v76, v247, v76
	v_cndmask_b32_e64 v0, v80, v0, s[4:5]
	s_waitcnt lgkmcnt(0)
	v_add_f32_e32 v0, v0, v76
	v_cndmask_b32_e64 v76, v65, v68, s[4:5]
	v_cndmask_b32_e64 v65, v68, v65, s[4:5]
	ds_bpermute_b32 v68, v247, v76
	s_waitcnt lgkmcnt(0)
	v_add_f32_e32 v65, v65, v68
	v_cndmask_b32_e64 v68, v35, v74, s[6:7]
	ds_bpermute_b32 v68, v246, v68
	v_cndmask_b32_e64 v35, v74, v35, s[6:7]
	s_waitcnt lgkmcnt(0)
	v_add_f32_e32 v35, v35, v68
	v_cndmask_b32_e64 v68, v36, v75, s[6:7]
	ds_bpermute_b32 v68, v246, v68
	v_cndmask_b32_e64 v36, v75, v36, s[6:7]
	s_waitcnt lgkmcnt(0)
	v_add_f32_e32 v36, v36, v68
	v_cndmask_b32_e64 v68, v37, v0, s[6:7]
	v_cndmask_b32_e64 v0, v0, v37, s[6:7]
	ds_bpermute_b32 v37, v246, v68
	s_waitcnt lgkmcnt(0)
	v_add_f32_e32 v0, v0, v37
	v_cndmask_b32_e64 v37, v64, v65, s[6:7]
	ds_bpermute_b32 v37, v246, v37
	v_cndmask_b32_e64 v64, v65, v64, s[6:7]
	s_waitcnt lgkmcnt(0)
	v_add_f32_e32 v37, v64, v37
	v_cndmask_b32_e64 v64, v35, v0, s[8:9]
	v_cndmask_b32_e64 v0, v0, v35, s[8:9]
	ds_bpermute_b32 v35, v245, v64
	s_waitcnt lgkmcnt(0)
	v_add_f32_e32 v0, v0, v35
	v_cndmask_b32_e64 v35, v36, v37, s[8:9]
	ds_bpermute_b32 v35, v245, v35
	v_cndmask_b32_e64 v36, v37, v36, s[8:9]
	s_waitcnt lgkmcnt(0)
	v_add_f32_e32 v35, v36, v35
	v_cndmask_b32_e64 v36, v0, v35, s[10:11]
	v_cndmask_b32_e64 v0, v35, v0, s[10:11]
	ds_bpermute_b32 v35, v244, v36
	s_waitcnt lgkmcnt(0)
	v_add_f32_e32 v0, v0, v35
	ds_bpermute_b32 v35, v243, v0
	s_waitcnt lgkmcnt(0)
	v_add_f32_e32 v0, v0, v35
	ds_bpermute_b32 v35, v252, v0
	s_waitcnt lgkmcnt(0)
	v_add_f32_e32 v0, v0, v35
	ds_bpermute_b32 v35, v247, v0
	s_waitcnt lgkmcnt(0)
	v_max_f32_e32 v35, v35, v35
	v_max_f32_e32 v35, v0, v35
	ds_bpermute_b32 v36, v246, v35
	s_waitcnt lgkmcnt(0)
	v_max_f32_e32 v36, v36, v36
	v_max_f32_e32 v35, v35, v36
	ds_bpermute_b32 v36, v245, v35
	s_waitcnt lgkmcnt(0)
	v_max_f32_e32 v36, v36, v36
	v_max_f32_e32 v35, v35, v36
	ds_bpermute_b32 v36, v244, v35
	s_waitcnt lgkmcnt(0)
	v_max_f32_e32 v36, v36, v36
	v_max_f32_e32 v35, v35, v36
	v_sub_f32_e32 v0, v0, v35
	v_mul_f32_e32 v35, 0x3fb8aa3b, v0
	v_fma_f32 v36, v0, s25, -v35
	v_rndne_f32_e32 v37, v35
	v_fmac_f32_e32 v36, 0x32a5705f, v0
	v_sub_f32_e32 v35, v35, v37
	v_add_f32_e32 v35, v35, v36
	v_exp_f32_e32 v35, v35
	v_cvt_i32_f32_e32 v36, v37
	s_mov_b32 s25, 0xc2ce8ed0
	v_cmp_ngt_f32_e32 vcc, s25, v0
	s_mov_b32 s25, 0x42b17218
	v_ldexp_f32 v35, v35, v36
	v_cndmask_b32_e32 v35, 0, v35, vcc
	v_cmp_nlt_f32_e32 vcc, s25, v0
	s_nop 1
	v_cndmask_b32_e32 v0, v240, v35, vcc
	ds_bpermute_b32 v35, v247, v0
	s_waitcnt lgkmcnt(0)
	v_add_f32_e32 v35, v0, v35
	ds_bpermute_b32 v36, v246, v35
	s_waitcnt lgkmcnt(0)
	v_add_f32_e32 v35, v35, v36
	ds_bpermute_b32 v36, v245, v35
	s_waitcnt lgkmcnt(0)
	v_add_f32_e32 v35, v35, v36
	ds_bpermute_b32 v36, v244, v35
	s_and_saveexec_b64 s[26:27], s[12:13]
	s_cbranch_execz .LBB0_1431
	s_waitcnt lgkmcnt(0)
	v_add_f32_e32 v35, v35, v36
	v_div_scale_f32 v36, s[28:29], v35, v35, v0
	v_rcp_f32_e32 v37, v36
	v_div_scale_f32 v64, vcc, v0, v35, v0
	v_fma_f32 v65, -v36, v37, 1.0
	v_fmac_f32_e32 v37, v65, v37
	v_mul_f32_e32 v65, v64, v37
	v_fma_f32 v68, -v36, v65, v64
	v_fmac_f32_e32 v65, v68, v37
	v_fma_f32 v36, -v36, v65, v64
	v_div_fmas_f32 v36, v36, v37, v65
	v_div_fixup_f32 v0, v36, v35, v0
	global_store_dword v[46:47], v0, off offset:-64
